# late gate-column GEMM tile k-loop: x rows prefetched one k-tile ahead into spare VGPRs, per-column vectors fetched in one batch (1 round trip per k-tile instead of 5); adaLN k-loop 4 groups per trip
# speedup vs baseline: 1.0087x; 1.0087x over previous
; __device__ __forceinline__ void gemm_late_tile(const Params& p, int l, int mt_, int nt_, unsigned char* smem) {
;     ...
;   const int lrow = tid >> 3, lkc = tid & 7;
;   const int bb = m0 / TPB, pp0 = m0 % TPB;
;   const bool isc0 = pp0 < 256;
;   const float* xbase;
;   if (l == 0) xbase = isc0 ? p.ctx + ((size_t)bb * 256 + pp0) * 1024 : p.x + ((size_t)bb * 4096 + pp0 - 256) * 1024;
;   else xbase = isc0 ? p.ctxcur + ((size_t)bb * 256 + pp0) * 1024 : p.out + ((size_t)bb * 4096 + pp0 - 256) * 1024;
;   const float* xr = xbase + (size_t)lrow * 1024 + lkc * 8;
;   const float* md = p.mod + (size_t)(l * 5 + (isc0 ? 4 : bb)) * 3072 + lkc * 8;
;   const float* nwp = p.norm_w + l * 1024 + lkc * 8;
;   const float rs0 = p.rstd[m0 + lrow], rs1 = p.rstd[m0 + lrow + 32], rs2 = p.rstd[m0 + lrow + 64], rs3 = p.rstd[m0 + lrow + 96];
;   const bf16_t* Bg = Bt + (size_t)(n0 + lrow) * 1024 + lkc * 8;
;   float4 xa0, xb0, xa1, xb1, xa2, xb2, xa3, xb3, nwa, nwb, sca, scb, sha, shb;
;   uint4 lb0, lb1, lb2, lb3;
;     ...
;   L_LOAD(0);
;   L_STORE(0);
.LBB0_587:
	s_waitcnt vmcnt(0)
	v_ashrrev_i32_e32 v38, 3, v105
	v_ashrrev_i32_e32 v39, 31, v38
	v_lshlrev_b32_e32 v2, 3, v105
	v_lshlrev_b64 v[0:1], 12, v[38:39]
	v_and_b32_e32 v104, 56, v2
	s_mul_i32 s67, s67, 5
	v_lshl_add_u64 v[0:1], s[56:57], 0, v[0:1]
	v_lshlrev_b32_e32 v28, 2, v104
	v_mov_b32_e32 v29, v164
	s_sub_i32 s55, s66, s67
	v_lshl_add_u64 v[108:109], v[0:1], 0, v[28:29]
	v_add_u32_e32 v0, s28, v38
	s_lshl_b32 s54, s55, 7
	v_ashrrev_i32_e32 v1, 31, v0
	s_addk_i32 s54, 0x800
	v_lshl_add_u64 v[0:1], v[0:1], 2, s[86:87]
	global_load_dword v100, v[0:1], off
	global_load_dword v98, v[0:1], off offset:128
	global_load_dword v96, v[0:1], off offset:256
	global_load_dword v106, v[0:1], off offset:384
	v_add_u32_e32 v0, s54, v38
	v_ashrrev_i32_e32 v1, 31, v0
	v_lshlrev_b64 v[0:1], 11, v[0:1]
	v_lshl_add_u64 v[0:1], s[44:45], 0, v[0:1]
	v_lshlrev_b32_e32 v56, 1, v104
	v_mov_b32_e32 v57, v164
	s_and_b64 s[50:51], s[50:51], exec
	v_readlane_b32 s0, v255, 40
	v_lshl_add_u64 v[120:121], v[0:1], 0, v[56:57]
	s_cselect_b32 s48, 4, s48
	v_readlane_b32 s1, v255, 41
	s_mul_i32 s49, s0, 5
	v_add_co_u32_e32 v4, vcc, s27, v120
	s_add_i32 s48, s48, s49
	v_readlane_b32 s0, v251, 48
	v_addc_co_u32_e32 v5, vcc, 0, v121, vcc
	s_mul_hi_i32 s49, s48, 0x3000
	s_mulk_i32 s48, 0x3000
	v_readlane_b32 s1, v251, 49
	v_readlane_b32 s2, v251, 50
	v_add_co_u32_e32 v8, vcc, s26, v120
	v_readlane_b32 s3, v251, 51
	s_add_u32 s48, s2, s48
	s_mov_b64 s[0:1], 0x20000
	v_addc_co_u32_e32 v9, vcc, 0, v121, vcc
	s_addc_u32 s49, s3, s49
	v_lshl_add_u64 v[34:35], v[108:109], 0, s[0:1]
	s_mov_b64 s[0:1], 0x40000
	v_add_co_u32_e32 v12, vcc, s90, v120
	v_lshl_add_u64 v[102:103], s[48:49], 0, v[28:29]
	v_lshl_add_u64 v[32:33], v[108:109], 0, s[0:1]
	s_mov_b64 s[0:1], 0x60000
	v_addc_co_u32_e32 v13, vcc, 0, v121, vcc
	v_lshl_add_u64 v[36:37], v[108:109], 0, s[0:1]
	s_mov_b64 s[0:1], 0x1000
	v_add_co_u32_e32 v116, vcc, s31, v102
	global_load_dwordx4 v[0:3], v[120:121], off
	v_lshl_add_u64 v[24:25], v[102:103], 0, s[0:1]
	global_load_dwordx4 v[4:7], v[4:5], off
	v_addc_co_u32_e32 v117, vcc, 0, v103, vcc
	global_load_dwordx4 v[8:11], v[8:9], off
	v_lshl_add_u64 v[110:111], s[46:47], 0, v[28:29]
	global_load_dwordx4 v[12:15], v[12:13], off
	s_nop 0
	global_load_dwordx4 v[44:47], v[108:109], off offset:16
	global_load_dwordx4 v[40:43], v[108:109], off
	global_load_dwordx4 v[16:19], v28, s[46:47] offset:16
	global_load_dwordx4 v[20:23], v28, s[46:47]
	global_load_dwordx4 v[48:51], v[116:117], off
	global_load_dwordx4 v[52:55], v[24:25], off offset:16
	s_nop 0
	global_load_dwordx4 v[24:27], v28, s[48:49] offset:16
	s_nop 0
	global_load_dwordx4 v[28:31], v28, s[48:49]
	s_movk_i32 s0, 0x90
	v_mul_lo_u32 v38, v38, s0
	v_add3_u32 v141, 0, v38, v56
	v_add_co_u32_e32 v114, vcc, s26, v108
	v_and_b32_e32 v139, 15, v105
	s_nop 0
	v_addc_co_u32_e32 v115, vcc, 0, v109, vcc
	v_add_co_u32_e32 v112, vcc, s91, v108
	v_and_b32_e32 v138, 63, v105
	s_nop 0
	v_addc_co_u32_e32 v113, vcc, 0, v109, vcc
	v_add_co_u32_e32 v118, vcc, s88, v108
	v_bfe_u32 v140, v105, 4, 2
	s_nop 0
	v_addc_co_u32_e32 v119, vcc, 0, v109, vcc
	s_mov_b64 s[48:49], 0
	s_mov_b64 s[50:51], 0
	v_readlane_b32 s4, v251, 52
	v_readlane_b32 s5, v251, 53
	v_readlane_b32 s6, v251, 54
	s_waitcnt vmcnt(15)
	v_mov_b32_e32 v101, v100
	s_waitcnt vmcnt(14)
	v_mov_b32_e32 v99, v98
	s_waitcnt vmcnt(13)
	v_mov_b32_e32 v97, v96
	s_waitcnt vmcnt(12)
	v_mov_b32_e32 v107, v106
	v_readlane_b32 s7, v251, 55
	v_readlane_b32 s8, v251, 56
	v_readlane_b32 s9, v251, 57
	v_readlane_b32 s10, v251, 58
	v_readlane_b32 s11, v251, 59
	v_readlane_b32 s12, v251, 60
	v_readlane_b32 s13, v251, 61
	v_readlane_b32 s14, v251, 62
	v_readlane_b32 s15, v251, 63
	s_waitcnt vmcnt(7)
	v_pk_mul_f32 v[44:45], v[100:101], v[44:45] op_sel_hi:[0,1]
	s_waitcnt vmcnt(6)
	v_pk_mul_f32 v[40:41], v[100:101], v[40:41] op_sel_hi:[0,1]
	v_pk_mul_f32 v[42:43], v[100:101], v[42:43] op_sel_hi:[0,1]
	s_waitcnt vmcnt(4)
	v_pk_mul_f32 v[58:59], v[40:41], v[20:21]
	s_waitcnt vmcnt(3)
	v_pk_add_f32 v[40:41], v[48:49], 1.0 op_sel_hi:[1,0]
	v_pk_mul_f32 v[46:47], v[100:101], v[46:47] op_sel_hi:[0,1]
	s_waitcnt vmcnt(0)
	v_pk_fma_f32 v[48:49], v[58:59], v[40:41], v[28:29]
	v_pk_mul_f32 v[58:59], v[42:43], v[22:23]
	v_pk_add_f32 v[42:43], v[50:51], 1.0 op_sel_hi:[1,0]
	v_cvt_pk_bf16_f32 v48, v48, v49
	v_pk_fma_f32 v[50:51], v[58:59], v[42:43], v[30:31]
	s_nop 0
	v_cvt_pk_bf16_f32 v49, v50, v51
	v_pk_mul_f32 v[50:51], v[44:45], v[16:17]
	v_pk_add_f32 v[44:45], v[52:53], 1.0 op_sel_hi:[1,0]
	v_pk_mul_f32 v[52:53], v[46:47], v[18:19]
	v_pk_add_f32 v[46:47], v[54:55], 1.0 op_sel_hi:[1,0]
	v_pk_fma_f32 v[50:51], v[50:51], v[44:45], v[24:25]
	v_pk_fma_f32 v[52:53], v[52:53], v[46:47], v[26:27]
	v_cvt_pk_bf16_f32 v50, v50, v51
	v_cvt_pk_bf16_f32 v51, v52, v53
	ds_write_b128 v141, v[48:51]
	global_load_dwordx4 v[48:51], v[114:115], off
	global_load_dwordx4 v[52:55], v[34:35], off offset:16
	s_waitcnt vmcnt(1)
	v_pk_mul_f32 v[34:35], v[98:99], v[48:49] op_sel_hi:[0,1]
	v_pk_mul_f32 v[34:35], v[34:35], v[20:21]
	s_nop 0
	v_pk_fma_f32 v[34:35], v[34:35], v[40:41], v[28:29]
	s_nop 0
	v_cvt_pk_bf16_f32 v48, v34, v35
	v_pk_mul_f32 v[34:35], v[98:99], v[50:51] op_sel_hi:[0,1]
	v_pk_mul_f32 v[34:35], v[34:35], v[22:23]
	s_nop 0
	v_pk_fma_f32 v[34:35], v[34:35], v[42:43], v[30:31]
	s_nop 0
	v_cvt_pk_bf16_f32 v49, v34, v35
	s_waitcnt vmcnt(0)
; __device__ __forceinline__ void gemm_late_tile(const Params& p, int l, int mt_, int nt_, unsigned char* smem) {
;     ...
;   f32x4 acc[4][4];
; #pragma unroll
;   for (int i = 0; i < 4; ++i)
; #pragma unroll
;     for (int j = 0; j < 4; ++j) acc[i][j] = (f32x4){0.f, 0.f, 0.f, 0.f};
;   const int lrow = tid >> 3, lkc = tid & 7;
;   const int bb = m0 / TPB, pp0 = m0 % TPB;
;   const bool isc0 = pp0 < 256;
;   const float* xbase;
;   if (l == 0) xbase = isc0 ? p.ctx + ((size_t)bb * 256 + pp0) * 1024 : p.x + ((size_t)bb * 4096 + pp0 - 256) * 1024;
;   else xbase = isc0 ? p.ctxcur + ((size_t)bb * 256 + pp0) * 1024 : p.out + ((size_t)bb * 4096 + pp0 - 256) * 1024;
;   const float* xr = xbase + (size_t)lrow * 1024 + lkc * 8;
;   const float* md = p.mod + (size_t)(l * 5 + (isc0 ? 4 : bb)) * 3072 + lkc * 8;
;   const float* nwp = p.norm_w + l * 1024 + lkc * 8;
;   const float rs0 = p.rstd[m0 + lrow], rs1 = p.rstd[m0 + lrow + 32], rs2 = p.rstd[m0 + lrow + 64], rs3 = p.rstd[m0 + lrow + 96];
;   const bf16_t* Bg = Bt + (size_t)(n0 + lrow) * 1024 + lkc * 8;
;   float4 xa0, xb0, xa1, xb1, xa2, xb2, xa3, xb3, nwa, nwb, sca, scb, sha, shb;
;   uint4 lb0, lb1, lb2, lb3;
;     ...
;   L_LOAD(0);
;   L_STORE(0);
;   __syncthreads();
;   for (int kt = 0; kt < 16; ++kt) {
;     L_LOAD((kt + 1 < 16) ? kt + 1 : 15);
	v_pk_mul_f32 v[34:35], v[98:99], v[52:53] op_sel_hi:[0,1]
	v_pk_mul_f32 v[34:35], v[34:35], v[16:17]
	s_nop 0
	v_pk_fma_f32 v[34:35], v[34:35], v[44:45], v[24:25]
	s_nop 0
	v_cvt_pk_bf16_f32 v50, v34, v35
	v_pk_mul_f32 v[34:35], v[98:99], v[54:55] op_sel_hi:[0,1]
	v_pk_mul_f32 v[34:35], v[34:35], v[18:19]
	s_nop 0
	v_pk_fma_f32 v[34:35], v[34:35], v[46:47], v[26:27]
	s_nop 0
	v_cvt_pk_bf16_f32 v51, v34, v35
	ds_write_b128 v141, v[48:51] offset:4608
	global_load_dwordx4 v[48:51], v[112:113], off
	s_nop 0
	global_load_dwordx4 v[32:35], v[32:33], off offset:16
	s_waitcnt vmcnt(1)
	v_pk_mul_f32 v[38:39], v[96:97], v[48:49] op_sel_hi:[0,1]
	s_waitcnt vmcnt(0)
	v_pk_mul_f32 v[32:33], v[96:97], v[32:33] op_sel_hi:[0,1]
	v_pk_mul_f32 v[38:39], v[38:39], v[20:21]
	v_pk_mul_f32 v[32:33], v[32:33], v[16:17]
	v_pk_fma_f32 v[38:39], v[38:39], v[40:41], v[28:29]
	v_pk_fma_f32 v[32:33], v[32:33], v[44:45], v[24:25]
	v_cvt_pk_bf16_f32 v48, v38, v39
	v_pk_mul_f32 v[38:39], v[96:97], v[50:51] op_sel_hi:[0,1]
	v_cvt_pk_bf16_f32 v50, v32, v33
	v_pk_mul_f32 v[32:33], v[96:97], v[34:35] op_sel_hi:[0,1]
	v_pk_mul_f32 v[38:39], v[38:39], v[22:23]
	v_pk_mul_f32 v[32:33], v[32:33], v[18:19]
	v_pk_fma_f32 v[38:39], v[38:39], v[42:43], v[30:31]
	v_pk_fma_f32 v[32:33], v[32:33], v[46:47], v[26:27]
	v_cvt_pk_bf16_f32 v49, v38, v39
	v_cvt_pk_bf16_f32 v51, v32, v33
	ds_write_b128 v141, v[48:51] offset:9216
	global_load_dwordx4 v[32:35], v[118:119], off
	s_nop 0
	global_load_dwordx4 v[36:39], v[36:37], off offset:16
	s_waitcnt vmcnt(1)
	v_pk_mul_f32 v[32:33], v[106:107], v[32:33] op_sel_hi:[0,1]
	v_pk_mul_f32 v[20:21], v[32:33], v[20:21]
	s_nop 0
	v_pk_fma_f32 v[20:21], v[20:21], v[40:41], v[28:29]
	v_pk_mul_f32 v[28:29], v[106:107], v[34:35] op_sel_hi:[0,1]
	v_pk_mul_f32 v[22:23], v[28:29], v[22:23]
	v_cvt_pk_bf16_f32 v20, v20, v21
	v_pk_fma_f32 v[22:23], v[22:23], v[42:43], v[30:31]
	s_nop 0
	v_cvt_pk_bf16_f32 v21, v22, v23
	s_waitcnt vmcnt(0)
	v_pk_mul_f32 v[22:23], v[106:107], v[36:37] op_sel_hi:[0,1]
	v_pk_mul_f32 v[16:17], v[22:23], v[16:17]
	s_nop 0
	v_pk_fma_f32 v[16:17], v[16:17], v[44:45], v[24:25]
	s_nop 0
	v_cvt_pk_bf16_f32 v22, v16, v17
	v_pk_mul_f32 v[16:17], v[106:107], v[38:39] op_sel_hi:[0,1]
	v_pk_mul_f32 v[16:17], v[16:17], v[18:19]
	s_nop 0
	v_pk_fma_f32 v[16:17], v[16:17], v[46:47], v[26:27]
	s_nop 0
	v_cvt_pk_bf16_f32 v23, v16, v17
	ds_write_b128 v141, v[20:23] offset:13824
	ds_write_b128 v141, v[0:3] offset:36864
	ds_write_b128 v141, v[4:7] offset:41472
	ds_write_b128 v141, v[8:11] offset:46080
	ds_write_b128 v141, v[12:15] offset:50688
	v_ashrrev_i32_e32 v0, 1, v105
	v_and_b32_e32 v142, 0xffffffc0, v0
	v_or_b32_e32 v0, v142, v139
	v_mul_lo_u32 v0, v0, s0
	v_and_b32_e32 v1, 48, v105
	v_add3_u32 v144, 0, v0, v1
	v_and_b32_e32 v0, 0x4f, v105
	v_mul_u32_u24_e32 v0, 0x90, v0
	v_add3_u32 v143, 0, v0, v1
	v_mov_b32_e32 v0, 0
	v_mov_b32_e32 v1, v0
	v_mov_b32_e32 v2, v0
	v_mov_b32_e32 v3, v0
	v_mov_b32_e32 v4, v0
	v_mov_b32_e32 v5, v0
	v_mov_b32_e32 v6, v0
	v_mov_b32_e32 v7, v0
	v_mov_b32_e32 v8, v0
	v_mov_b32_e32 v9, v0
	v_mov_b32_e32 v10, v0
	v_mov_b32_e32 v11, v0
	v_mov_b32_e32 v12, v0
	v_mov_b32_e32 v13, v0
	v_mov_b32_e32 v14, v0
	v_mov_b32_e32 v15, v0
	v_mov_b32_e32 v16, v0
	v_mov_b32_e32 v17, v0
	v_mov_b32_e32 v18, v0
	v_mov_b32_e32 v19, v0
	v_mov_b32_e32 v20, v0
	v_mov_b32_e32 v21, v0
	v_mov_b32_e32 v22, v0
	v_mov_b32_e32 v23, v0
	v_mov_b32_e32 v24, v0
	v_mov_b32_e32 v25, v0
	v_mov_b32_e32 v26, v0
	v_mov_b32_e32 v27, v0
	v_mov_b32_e32 v28, v0
	v_mov_b32_e32 v29, v0
	v_mov_b32_e32 v30, v0
	v_mov_b32_e32 v31, v0
	v_mov_b32_e32 v32, v0
	v_mov_b32_e32 v33, v0
	v_mov_b32_e32 v34, v0
	v_mov_b32_e32 v35, v0
	v_mov_b32_e32 v36, v0
	v_mov_b32_e32 v37, v0
	v_mov_b32_e32 v38, v0
	v_mov_b32_e32 v39, v0
	v_mov_b32_e32 v40, v0
	v_mov_b32_e32 v41, v0
	v_mov_b32_e32 v42, v0
	v_mov_b32_e32 v43, v0
	v_mov_b32_e32 v44, v0
	v_mov_b32_e32 v45, v0
	v_mov_b32_e32 v46, v0
	v_mov_b32_e32 v47, v0
	v_mov_b32_e32 v48, v0
	v_mov_b32_e32 v49, v0
	v_mov_b32_e32 v50, v0
	v_mov_b32_e32 v51, v0
	v_mov_b32_e32 v52, v0
	v_mov_b32_e32 v53, v0
	v_mov_b32_e32 v54, v0
	v_mov_b32_e32 v55, v0
	v_mov_b32_e32 v56, v0
	v_mov_b32_e32 v57, v0
	v_mov_b32_e32 v58, v0
	v_mov_b32_e32 v59, v0
	v_mov_b32_e32 v60, v0
	v_mov_b32_e32 v61, v0
	v_mov_b32_e32 v62, v0
	v_mov_b32_e32 v63, v0
	v_lshl_add_u64 v[160:161], v[108:109], 0, s[16:17]
	v_lshl_add_u64 v[216:217], v[108:109], 0, s[24:25]
	v_lshl_add_u64 v[218:219], v[108:109], 0, s[18:19]
	global_load_dwordx4 v[220:223], v[108:109], off offset:256
	global_load_dwordx4 v[224:227], v[108:109], off offset:272
	global_load_dwordx4 v[228:231], v[160:161], off
	global_load_dwordx4 v[232:235], v[160:161], off offset:16
	global_load_dwordx4 v[238:241], v[216:217], off
	global_load_dwordx4 v[242:245], v[216:217], off offset:16
	global_load_dwordx4 v[246:249], v[218:219], off
	s_waitcnt lgkmcnt(0)
	s_barrier
.LBB0_588:
	v_lshl_add_u64 v[76:77], v[120:121], 0, s[50:51]
	v_add_co_u32_e32 v68, vcc, s27, v76
	s_and_b32 s56, s50, 0x80
	s_nop 0
	v_addc_co_u32_e32 v69, vcc, 0, v77, vcc
	v_add_co_u32_e32 v72, vcc, s26, v76
	global_load_dwordx4 v[64:67], v[76:77], off offset:128
	s_nop 0
	v_addc_co_u32_e32 v73, vcc, 0, v77, vcc
	v_add_co_u32_e32 v76, vcc, s90, v76
	s_mulk_i32 s56, 0x90
	s_nop 0
	v_addc_co_u32_e32 v77, vcc, 0, v77, vcc
	v_add_u32_e32 v86, s56, v144
	global_load_dwordx4 v[68:71], v[68:69], off offset:128
	v_add_u32_e32 v87, s56, v143
	global_load_dwordx4 v[72:75], v[72:73], off offset:128
	v_lshl_add_u64 v[92:93], v[102:103], 0, s[48:49]
	global_load_dwordx4 v[76:79], v[76:77], off offset:128
	ds_read_b128 v[80:83], v86
	ds_read_b128 v[130:133], v87 offset:36864
	ds_read_b128 v[134:137], v86 offset:2304
	ds_read_b128 v[146:149], v87 offset:39168
	ds_read_b128 v[150:153], v86 offset:4608
	ds_read_b128 v[154:157], v87 offset:41472
	ds_read_b128 v[158:161], v86 offset:6912
	ds_read_b128 v[216:219], v87 offset:43776
	s_waitcnt lgkmcnt(6)
	v_mfma_f32_16x16x32_bf16 v[60:63], v[80:83], v[130:133], v[60:63]
	v_lshl_add_u64 v[124:125], v[108:109], 0, s[48:49]
	v_lshl_add_u64 v[84:85], v[110:111], 0, s[48:49]
	v_add_co_u32_e32 v90, vcc, s31, v92
	s_waitcnt lgkmcnt(4)
	v_mfma_f32_16x16x32_bf16 v[56:59], v[80:83], v[146:149], v[56:59]
	v_lshl_add_u64 v[88:89], v[92:93], 0, s[22:23]
	v_addc_co_u32_e32 v91, vcc, 0, v93, vcc
	s_waitcnt lgkmcnt(2)
	v_mfma_f32_16x16x32_bf16 v[52:55], v[80:83], v[154:157], v[52:55]
	s_add_u32 s50, s50, 0x80
	s_addc_u32 s51, s51, 0
	s_and_b32 s56, s50, 0x80
	s_waitcnt lgkmcnt(0)
	v_mfma_f32_16x16x32_bf16 v[48:51], v[80:83], v[216:219], v[48:51]
	s_mulk_i32 s56, 0x90
	v_add_u32_e32 v145, s56, v141
	v_lshl_add_u64 v[128:129], v[124:125], 0, s[16:17]
	v_mfma_f32_16x16x32_bf16 v[44:47], v[134:137], v[130:133], v[44:47]
	v_lshl_add_u64 v[126:127], v[124:125], 0, s[24:25]
	v_lshl_add_u64 v[122:123], v[124:125], 0, s[18:19]
	s_add_u32 s48, s48, 0x100
	v_mfma_f32_16x16x32_bf16 v[40:43], v[134:137], v[146:149], v[40:43]
	s_addc_u32 s49, s49, 0
	s_cmpk_lg_i32 s48, 0xf00
	v_mfma_f32_16x16x32_bf16 v[36:39], v[134:137], v[154:157], v[36:39]
	v_mfma_f32_16x16x32_bf16 v[32:35], v[134:137], v[216:219], v[32:35]
	v_mfma_f32_16x16x32_bf16 v[28:31], v[150:153], v[130:133], v[28:31]
	v_mfma_f32_16x16x32_bf16 v[24:27], v[150:153], v[146:149], v[24:27]
	v_mfma_f32_16x16x32_bf16 v[20:23], v[150:153], v[154:157], v[20:23]
	v_mfma_f32_16x16x32_bf16 v[16:19], v[150:153], v[216:219], v[16:19]
	v_mfma_f32_16x16x32_bf16 v[12:15], v[158:161], v[130:133], v[12:15]
	v_mfma_f32_16x16x32_bf16 v[8:11], v[158:161], v[146:149], v[8:11]
	v_mfma_f32_16x16x32_bf16 v[4:7], v[158:161], v[154:157], v[4:7]
	v_mfma_f32_16x16x32_bf16 v[0:3], v[158:161], v[216:219], v[0:3]
	ds_read_b128 v[80:83], v86 offset:64
	ds_read_b128 v[130:133], v87 offset:36928
	ds_read_b128 v[134:137], v86 offset:2368
	ds_read_b128 v[146:149], v87 offset:39232
	ds_read_b128 v[150:153], v86 offset:4672
	ds_read_b128 v[154:157], v87 offset:41536
	ds_read_b128 v[158:161], v86 offset:6976
	ds_read_b128 v[216:219], v87 offset:43840
	s_waitcnt lgkmcnt(6)
	v_mfma_f32_16x16x32_bf16 v[60:63], v[80:83], v[130:133], v[60:63]
	s_waitcnt lgkmcnt(4)
	v_mfma_f32_16x16x32_bf16 v[56:59], v[80:83], v[146:149], v[56:59]
	s_waitcnt lgkmcnt(2)
	v_mfma_f32_16x16x32_bf16 v[52:55], v[80:83], v[154:157], v[52:55]
	s_waitcnt lgkmcnt(0)
	v_mfma_f32_16x16x32_bf16 v[48:51], v[80:83], v[216:219], v[48:51]
	v_mfma_f32_16x16x32_bf16 v[44:47], v[134:137], v[130:133], v[44:47]
	v_mfma_f32_16x16x32_bf16 v[40:43], v[134:137], v[146:149], v[40:43]
	v_mfma_f32_16x16x32_bf16 v[36:39], v[134:137], v[154:157], v[36:39]
	v_mfma_f32_16x16x32_bf16 v[32:35], v[134:137], v[216:219], v[32:35]
	v_mfma_f32_16x16x32_bf16 v[28:31], v[150:153], v[130:133], v[28:31]
	v_mfma_f32_16x16x32_bf16 v[12:15], v[158:161], v[130:133], v[12:15]
	v_mfma_f32_16x16x32_bf16 v[24:27], v[150:153], v[146:149], v[24:27]
	v_mfma_f32_16x16x32_bf16 v[20:23], v[150:153], v[154:157], v[20:23]
	v_mfma_f32_16x16x32_bf16 v[16:19], v[150:153], v[216:219], v[16:19]
	v_mfma_f32_16x16x32_bf16 v[8:11], v[158:161], v[146:149], v[8:11]
	v_mfma_f32_16x16x32_bf16 v[4:7], v[158:161], v[154:157], v[4:7]
	v_mfma_f32_16x16x32_bf16 v[0:3], v[158:161], v[216:219], v[0:3]
	global_load_dwordx4 v[80:83], v[84:85], off offset:272
	s_nop 0
	global_load_dwordx4 v[84:87], v[84:85], off offset:256
	global_load_dwordx4 v[146:149], v[90:91], off offset:256
	global_load_dwordx4 v[150:153], v[88:89], off offset:16
	s_nop 0
	global_load_dwordx4 v[88:91], v[92:93], off offset:272
	s_nop 0
	global_load_dwordx4 v[92:95], v[92:93], off offset:256
	global_load_dwordx4 v[154:157], v[122:123], off offset:16
	s_waitcnt vmcnt(1)
	v_pk_add_f32 v[130:131], v[146:147], 1.0 op_sel_hi:[1,0]
	v_pk_add_f32 v[132:133], v[148:149], 1.0 op_sel_hi:[1,0]
	v_pk_add_f32 v[134:135], v[150:151], 1.0 op_sel_hi:[1,0]
	v_pk_add_f32 v[136:137], v[152:153], 1.0 op_sel_hi:[1,0]
	v_pk_mul_f32 v[158:159], v[100:101], v[220:221]
	v_pk_mul_f32 v[160:161], v[100:101], v[222:223]
	v_pk_mul_f32 v[216:217], v[100:101], v[224:225]
	v_pk_mul_f32 v[218:219], v[100:101], v[226:227]
	v_pk_mul_f32 v[158:159], v[158:159], v[84:85]
	v_pk_mul_f32 v[160:161], v[160:161], v[86:87]
	v_pk_mul_f32 v[216:217], v[216:217], v[80:81]
	v_pk_mul_f32 v[218:219], v[218:219], v[82:83]
	v_pk_fma_f32 v[158:159], v[158:159], v[130:131], v[92:93]
	v_pk_fma_f32 v[160:161], v[160:161], v[132:133], v[94:95]
	v_pk_fma_f32 v[216:217], v[216:217], v[134:135], v[88:89]
	v_pk_fma_f32 v[218:219], v[218:219], v[136:137], v[90:91]
	v_cvt_pk_bf16_f32 v146, v158, v159
	v_cvt_pk_bf16_f32 v147, v160, v161
	v_cvt_pk_bf16_f32 v148, v216, v217
	v_cvt_pk_bf16_f32 v149, v218, v219
	ds_write_b128 v145, v[146:149]
	v_pk_mul_f32 v[158:159], v[98:99], v[228:229]
	v_pk_mul_f32 v[160:161], v[98:99], v[230:231]
	v_pk_mul_f32 v[216:217], v[98:99], v[232:233]
	v_pk_mul_f32 v[218:219], v[98:99], v[234:235]
	v_pk_mul_f32 v[158:159], v[158:159], v[84:85]
	v_pk_mul_f32 v[160:161], v[160:161], v[86:87]
	v_pk_mul_f32 v[216:217], v[216:217], v[80:81]
	v_pk_mul_f32 v[218:219], v[218:219], v[82:83]
	v_pk_fma_f32 v[158:159], v[158:159], v[130:131], v[92:93]
	v_pk_fma_f32 v[160:161], v[160:161], v[132:133], v[94:95]
	v_pk_fma_f32 v[216:217], v[216:217], v[134:135], v[88:89]
	v_pk_fma_f32 v[218:219], v[218:219], v[136:137], v[90:91]
	v_cvt_pk_bf16_f32 v150, v158, v159
	v_cvt_pk_bf16_f32 v151, v160, v161
	v_cvt_pk_bf16_f32 v152, v216, v217
	v_cvt_pk_bf16_f32 v153, v218, v219
	ds_write_b128 v145, v[150:153] offset:4608
	v_pk_mul_f32 v[158:159], v[96:97], v[238:239]
	v_pk_mul_f32 v[160:161], v[96:97], v[240:241]
	v_pk_mul_f32 v[216:217], v[96:97], v[242:243]
	v_pk_mul_f32 v[218:219], v[96:97], v[244:245]
	v_pk_mul_f32 v[158:159], v[158:159], v[84:85]
	v_pk_mul_f32 v[160:161], v[160:161], v[86:87]
	v_pk_mul_f32 v[216:217], v[216:217], v[80:81]
	v_pk_mul_f32 v[218:219], v[218:219], v[82:83]
	v_pk_fma_f32 v[158:159], v[158:159], v[130:131], v[92:93]
	v_pk_fma_f32 v[160:161], v[160:161], v[132:133], v[94:95]
	v_pk_fma_f32 v[216:217], v[216:217], v[134:135], v[88:89]
	v_pk_fma_f32 v[218:219], v[218:219], v[136:137], v[90:91]
	v_cvt_pk_bf16_f32 v126, v158, v159
	v_cvt_pk_bf16_f32 v127, v160, v161
	v_cvt_pk_bf16_f32 v128, v216, v217
	v_cvt_pk_bf16_f32 v129, v218, v219
	ds_write_b128 v145, v[126:129] offset:9216
	s_waitcnt vmcnt(0)
	v_pk_mul_f32 v[158:159], v[106:107], v[246:247]
	v_pk_mul_f32 v[160:161], v[106:107], v[248:249]
	v_pk_mul_f32 v[216:217], v[106:107], v[154:155]
	v_pk_mul_f32 v[218:219], v[106:107], v[156:157]
	v_pk_mul_f32 v[158:159], v[158:159], v[84:85]
	v_pk_mul_f32 v[160:161], v[160:161], v[86:87]
	v_pk_mul_f32 v[216:217], v[216:217], v[80:81]
	v_pk_mul_f32 v[218:219], v[218:219], v[82:83]
	v_pk_fma_f32 v[158:159], v[158:159], v[130:131], v[92:93]
	v_pk_fma_f32 v[160:161], v[160:161], v[132:133], v[94:95]
	v_pk_fma_f32 v[216:217], v[216:217], v[134:135], v[88:89]
	v_pk_fma_f32 v[218:219], v[218:219], v[136:137], v[90:91]
	v_cvt_pk_bf16_f32 v122, v158, v159
	v_cvt_pk_bf16_f32 v123, v160, v161
	v_cvt_pk_bf16_f32 v124, v216, v217
	v_cvt_pk_bf16_f32 v125, v218, v219
	ds_write_b128 v145, v[122:125] offset:13824
	ds_write_b128 v145, v[64:67] offset:36864
	ds_write_b128 v145, v[68:71] offset:41472
	ds_write_b128 v145, v[72:75] offset:46080
	ds_write_b128 v145, v[76:79] offset:50688
	s_cbranch_scc0 .Llate_nopf
	v_lshl_add_u64 v[158:159], v[108:109], 0, s[48:49]
	v_lshl_add_u64 v[216:217], v[158:159], 0, s[24:25]
	v_lshl_add_u64 v[218:219], v[158:159], 0, s[18:19]
	v_lshl_add_u64 v[160:161], v[158:159], 0, s[16:17]
	global_load_dwordx4 v[220:223], v[158:159], off offset:256
	global_load_dwordx4 v[224:227], v[158:159], off offset:272
	global_load_dwordx4 v[228:231], v[160:161], off
	global_load_dwordx4 v[232:235], v[160:161], off offset:16
	global_load_dwordx4 v[238:241], v[216:217], off
	global_load_dwordx4 v[242:245], v[216:217], off offset:16
	global_load_dwordx4 v[246:249], v[218:219], off
; __device__ __forceinline__ void gemm_late_tile(const Params& p, int l, int mt_, int nt_, unsigned char* smem) {
;     ...
;   for (int kt = 0; kt < 16; ++kt) {
;     L_LOAD((kt + 1 < 16) ? kt + 1 : 15);
;     G_COMPUTE(kt & 1);
;     L_STORE((kt + 1) & 1);
;     __syncthreads();
;   }
.Llate_nopf:
	s_waitcnt lgkmcnt(0)
	s_barrier
	s_cbranch_scc1 .LBB0_588
	v_add_co_u32_e32 v68, vcc, 0x10000, v120
	global_load_dwordx4 v[64:67], v[120:121], off offset:1920
	s_nop 0
	v_addc_co_u32_e32 v69, vcc, 0, v121, vcc
	v_add_co_u32_e32 v72, vcc, 0x20000, v120
	global_load_dwordx4 v[68:71], v[68:69], off offset:1920
	s_nop 0
	v_addc_co_u32_e32 v73, vcc, 0, v121, vcc
	v_add_co_u32_e32 v76, vcc, 0x30000, v120
	global_load_dwordx4 v[72:75], v[72:73], off offset:1920
	s_nop 0
	v_addc_co_u32_e32 v77, vcc, 0, v121, vcc
	global_load_dwordx4 v[76:79], v[76:77], off offset:1920
	ds_read_b128 v[80:83], v144 offset:18432
	ds_read_b128 v[84:87], v143 offset:55296
	ds_read_b128 v[90:93], v144 offset:20736
	ds_read_b128 v[130:133], v143 offset:57600
	ds_read_b128 v[134:137], v144 offset:23040
	ds_read_b128 v[146:149], v143 offset:59904
	ds_read_b128 v[150:153], v144 offset:25344
	ds_read_b128 v[154:157], v143 offset:62208
	s_mov_b64 s[0:1], 0x20f00
	s_waitcnt lgkmcnt(6)
	v_mfma_f32_16x16x32_bf16 v[60:63], v[80:83], v[84:87], v[60:63]
	v_lshl_add_u64 v[126:127], v[108:109], 0, s[0:1]
	s_mov_b64 s[0:1], 0x40f00
	v_lshl_add_u64 v[124:125], v[108:109], 0, s[0:1]
	s_waitcnt lgkmcnt(4)
	v_mfma_f32_16x16x32_bf16 v[56:59], v[80:83], v[130:133], v[56:59]
	s_mov_b64 s[0:1], 0x60f00
	v_lshl_add_u64 v[122:123], v[108:109], 0, s[0:1]
	s_mov_b64 s[0:1], 0x1f00
	s_waitcnt lgkmcnt(2)
	v_mfma_f32_16x16x32_bf16 v[52:55], v[80:83], v[146:149], v[52:55]
	v_lshl_add_u64 v[88:89], v[102:103], 0, s[0:1]
	s_cmp_lt_i32 s55, 0
	s_movk_i32 s0, 0xfc00
	s_waitcnt lgkmcnt(0)
	v_mfma_f32_16x16x32_bf16 v[48:51], v[80:83], v[154:157], v[48:51]
	s_cselect_b32 s48, s0, 0xfffff800
	v_readlane_b32 s0, v251, 48
	v_lshrrev_b32_e32 v128, 6, v105
	v_mfma_f32_16x16x32_bf16 v[44:47], v[90:93], v[84:87], v[44:47]
	s_movk_i32 s0, 0x2400
	v_readlane_b32 s10, v251, 58
	v_readlane_b32 s12, v251, 60
	v_mfma_f32_16x16x32_bf16 v[40:43], v[90:93], v[130:133], v[40:43]
	v_readlane_b32 s11, v251, 59
	v_readlane_b32 s13, v251, 61
	s_cselect_b32 s50, s10, s12
	v_mfma_f32_16x16x32_bf16 v[36:39], v[90:93], v[146:149], v[36:39]
	s_cselect_b32 s49, s11, s13
	v_readlane_b32 s1, v251, 49
	v_readlane_b32 s2, v251, 50
	v_mfma_f32_16x16x32_bf16 v[32:35], v[90:93], v[154:157], v[32:35]
	v_readlane_b32 s3, v251, 51
	v_readlane_b32 s4, v251, 52
	v_readlane_b32 s5, v251, 53
	v_mfma_f32_16x16x32_bf16 v[28:31], v[134:137], v[84:87], v[28:31]
	v_readlane_b32 s6, v251, 54
	v_readlane_b32 s7, v251, 55
	v_readlane_b32 s8, v251, 56
	v_mfma_f32_16x16x32_bf16 v[24:27], v[134:137], v[130:133], v[24:27]
	v_readlane_b32 s9, v251, 57
	v_readlane_b32 s14, v251, 62
	v_readlane_b32 s15, v251, 63
	v_mfma_f32_16x16x32_bf16 v[20:23], v[134:137], v[146:149], v[20:23]
	v_mfma_f32_16x16x32_bf16 v[16:19], v[134:137], v[154:157], v[16:19]
	v_mfma_f32_16x16x32_bf16 v[12:15], v[150:153], v[84:87], v[12:15]
	v_mfma_f32_16x16x32_bf16 v[8:11], v[150:153], v[130:133], v[8:11]
	v_mfma_f32_16x16x32_bf16 v[4:7], v[150:153], v[146:149], v[4:7]
	v_mfma_f32_16x16x32_bf16 v[0:3], v[150:153], v[154:157], v[0:3]
	ds_read_b128 v[80:83], v144 offset:18496
	ds_read_b128 v[84:87], v143 offset:55360
	ds_read_b128 v[90:93], v144 offset:20800
	ds_read_b128 v[130:133], v143 offset:57664
	ds_read_b128 v[134:137], v144 offset:23104
	ds_read_b128 v[146:149], v143 offset:59968
	ds_read_b128 v[150:153], v144 offset:25408
	ds_read_b128 v[154:157], v143 offset:62272
	s_waitcnt lgkmcnt(6)
	v_mfma_f32_16x16x32_bf16 v[60:63], v[80:83], v[84:87], v[60:63]
	s_waitcnt lgkmcnt(4)
	v_mfma_f32_16x16x32_bf16 v[56:59], v[80:83], v[130:133], v[56:59]
	s_waitcnt lgkmcnt(2)
	v_mfma_f32_16x16x32_bf16 v[52:55], v[80:83], v[146:149], v[52:55]
	s_nop 3
	v_cvt_pk_bf16_f32 v60, v60, s0
	s_nop 0
	v_cvt_pk_bf16_f32 v56, v56, s0
	s_waitcnt lgkmcnt(0)
	v_mfma_f32_16x16x32_bf16 v[48:51], v[80:83], v[154:157], v[48:51]
	v_mfma_f32_16x16x32_bf16 v[44:47], v[90:93], v[84:87], v[44:47]
	v_cvt_pk_bf16_f32 v52, v52, s0
	s_nop 5
	v_cvt_pk_bf16_f32 v48, v48, s0
	v_mfma_f32_16x16x32_bf16 v[40:43], v[90:93], v[130:133], v[40:43]
	v_mfma_f32_16x16x32_bf16 v[36:39], v[90:93], v[146:149], v[36:39]
	v_cvt_pk_bf16_f32 v44, v44, s0
	s_nop 5
	v_cvt_pk_bf16_f32 v40, v40, s0
	v_mfma_f32_16x16x32_bf16 v[32:35], v[90:93], v[154:157], v[32:35]
	v_mfma_f32_16x16x32_bf16 v[28:31], v[134:137], v[84:87], v[28:31]
	v_cvt_pk_bf16_f32 v36, v36, s0
	s_nop 5
	v_cvt_pk_bf16_f32 v32, v32, s0
	v_mfma_f32_16x16x32_bf16 v[24:27], v[134:137], v[130:133], v[24:27]
	v_mfma_f32_16x16x32_bf16 v[20:23], v[134:137], v[146:149], v[20:23]
	v_cvt_pk_bf16_f32 v28, v28, s0
	s_nop 5
	v_cvt_pk_bf16_f32 v24, v24, s0
	v_mfma_f32_16x16x32_bf16 v[16:19], v[134:137], v[154:157], v[16:19]
	v_mfma_f32_16x16x32_bf16 v[12:15], v[150:153], v[84:87], v[12:15]
	v_cvt_pk_bf16_f32 v20, v20, s0
	s_nop 5
	v_cvt_pk_bf16_f32 v16, v16, s0
	v_mfma_f32_16x16x32_bf16 v[8:11], v[150:153], v[130:133], v[8:11]
	v_mfma_f32_16x16x32_bf16 v[4:7], v[150:153], v[146:149], v[4:7]
	global_load_dwordx4 v[130:133], v[108:109], off offset:3856
	global_load_dwordx4 v[134:137], v[108:109], off offset:3840
	global_load_dwordx4 v[80:83], v[110:111], off offset:3856
	global_load_dwordx4 v[84:87], v[110:111], off offset:3840
	s_nop 0
	global_load_dwordx4 v[108:111], v[116:117], off offset:3840
	global_load_dwordx4 v[144:147], v[88:89], off offset:16
	s_nop 0
	global_load_dwordx4 v[88:91], v[102:103], off offset:3856
	global_load_dwordx4 v[92:95], v[102:103], off offset:3840
	v_cvt_pk_bf16_f32 v12, v12, s0
	v_cvt_pk_bf16_f32 v8, v8, s0
	v_mfma_f32_16x16x32_bf16 v[0:3], v[150:153], v[154:157], v[0:3]
	v_cvt_pk_bf16_f32 v4, v4, s0
	s_waitcnt vmcnt(6)
	v_pk_mul_f32 v[102:103], v[100:101], v[134:135]
	s_nop 4
	v_cvt_pk_bf16_f32 v0, v0, s0
	s_waitcnt vmcnt(4)
	v_pk_mul_f32 v[102:103], v[102:103], v[84:85]
	s_waitcnt vmcnt(3)
	v_pk_add_f32 v[108:109], v[108:109], 1.0 op_sel_hi:[1,0]
	v_pk_add_f32 v[110:111], v[110:111], 1.0 op_sel_hi:[1,0]
	s_waitcnt vmcnt(2)
	v_pk_add_f32 v[116:117], v[144:145], 1.0 op_sel_hi:[1,0]
	s_waitcnt vmcnt(0)
	v_pk_fma_f32 v[102:103], v[102:103], v[108:109], v[92:93]
	v_pk_add_f32 v[120:121], v[146:147], 1.0 op_sel_hi:[1,0]
	v_cvt_pk_bf16_f32 v134, v102, v103
	v_pk_mul_f32 v[102:103], v[100:101], v[136:137]
	s_nop 0
	v_pk_mul_f32 v[102:103], v[102:103], v[86:87]
	s_nop 0
	v_pk_fma_f32 v[102:103], v[102:103], v[110:111], v[94:95]
	s_nop 0
	v_cvt_pk_bf16_f32 v135, v102, v103
	v_pk_mul_f32 v[102:103], v[100:101], v[130:131]
	v_pk_mul_f32 v[100:101], v[100:101], v[132:133]
	v_pk_mul_f32 v[102:103], v[102:103], v[80:81]
	v_pk_mul_f32 v[100:101], v[100:101], v[82:83]
	v_pk_fma_f32 v[102:103], v[102:103], v[116:117], v[88:89]
	v_pk_fma_f32 v[100:101], v[100:101], v[120:121], v[90:91]
	v_cvt_pk_bf16_f32 v136, v102, v103
	v_cvt_pk_bf16_f32 v137, v100, v101
	ds_write_b128 v141, v[134:137]
	global_load_dwordx4 v[100:103], v[114:115], off offset:3840
	global_load_dwordx4 v[130:133], v[126:127], off offset:16
	s_waitcnt vmcnt(1)
	v_pk_mul_f32 v[100:101], v[98:99], v[100:101]
	v_pk_mul_f32 v[102:103], v[98:99], v[102:103]
	v_pk_mul_f32 v[100:101], v[100:101], v[84:85]
	v_pk_mul_f32 v[102:103], v[102:103], v[86:87]
	v_pk_fma_f32 v[100:101], v[100:101], v[108:109], v[92:93]
	v_pk_fma_f32 v[102:103], v[102:103], v[110:111], v[94:95]
	v_cvt_pk_bf16_f32 v100, v100, v101
	v_cvt_pk_bf16_f32 v101, v102, v103
	s_waitcnt vmcnt(0)
	v_pk_mul_f32 v[102:103], v[98:99], v[130:131]
	v_pk_mul_f32 v[98:99], v[98:99], v[132:133]
	v_pk_mul_f32 v[102:103], v[102:103], v[80:81]
	v_pk_mul_f32 v[98:99], v[98:99], v[82:83]
	v_pk_fma_f32 v[102:103], v[102:103], v[116:117], v[88:89]
	v_pk_fma_f32 v[98:99], v[98:99], v[120:121], v[90:91]
	v_cvt_pk_bf16_f32 v102, v102, v103
	v_cvt_pk_bf16_f32 v103, v98, v99
	ds_write_b128 v141, v[100:103] offset:4608
	global_load_dwordx4 v[98:101], v[112:113], off offset:3840
	s_nop 0
	global_load_dwordx4 v[112:115], v[124:125], off offset:16
	s_waitcnt vmcnt(1)
	v_pk_mul_f32 v[98:99], v[96:97], v[98:99]
	v_pk_mul_f32 v[100:101], v[96:97], v[100:101]
	v_pk_mul_f32 v[98:99], v[98:99], v[84:85]
	v_pk_mul_f32 v[100:101], v[100:101], v[86:87]
	v_pk_fma_f32 v[98:99], v[98:99], v[108:109], v[92:93]
	v_pk_fma_f32 v[100:101], v[100:101], v[110:111], v[94:95]
	v_cvt_pk_bf16_f32 v98, v98, v99
	v_cvt_pk_bf16_f32 v99, v100, v101
	s_waitcnt vmcnt(0)
	v_pk_mul_f32 v[100:101], v[96:97], v[112:113]
	v_pk_mul_f32 v[96:97], v[96:97], v[114:115]
	v_pk_mul_f32 v[100:101], v[100:101], v[80:81]
	v_pk_mul_f32 v[96:97], v[96:97], v[82:83]
	v_pk_fma_f32 v[100:101], v[100:101], v[116:117], v[88:89]
	v_pk_fma_f32 v[96:97], v[96:97], v[120:121], v[90:91]
	v_cvt_pk_bf16_f32 v100, v100, v101
	v_cvt_pk_bf16_f32 v101, v96, v97
	ds_write_b128 v141, v[98:101] offset:9216
	global_load_dwordx4 v[96:99], v[118:119], off offset:3840
	global_load_dwordx4 v[100:103], v[122:123], off offset:16
	s_waitcnt vmcnt(1)
	v_pk_mul_f32 v[96:97], v[106:107], v[96:97]
	s_nop 0
	v_pk_mul_f32 v[84:85], v[96:97], v[84:85]
	s_nop 0
	v_pk_fma_f32 v[84:85], v[84:85], v[108:109], v[92:93]
	v_pk_mul_f32 v[92:93], v[106:107], v[98:99]
	v_cvt_pk_bf16_f32 v84, v84, v85
	v_pk_mul_f32 v[86:87], v[92:93], v[86:87]
	s_nop 0
	v_pk_fma_f32 v[86:87], v[86:87], v[110:111], v[94:95]
	s_nop 0
	v_cvt_pk_bf16_f32 v85, v86, v87
	s_waitcnt vmcnt(0)
	v_pk_mul_f32 v[86:87], v[106:107], v[100:101]
	s_nop 0
	v_pk_mul_f32 v[80:81], v[86:87], v[80:81]
	s_nop 0
	v_pk_fma_f32 v[80:81], v[80:81], v[116:117], v[88:89]
	s_nop 0
	v_cvt_pk_bf16_f32 v86, v80, v81
	v_pk_mul_f32 v[80:81], v[106:107], v[102:103]
	s_nop 0
	v_pk_mul_f32 v[80:81], v[80:81], v[82:83]
	s_nop 0
	v_pk_fma_f32 v[80:81], v[80:81], v[120:121], v[90:91]
	s_nop 0
	v_cvt_pk_bf16_f32 v87, v80, v81
	ds_write_b128 v141, v[84:87] offset:13824
	ds_write_b128 v141, v[64:67] offset:36864
	ds_write_b128 v141, v[68:71] offset:41472
	ds_write_b128 v141, v[72:75] offset:46080
	ds_write_b128 v141, v[76:79] offset:50688
	v_mul_lo_u32 v66, v128, s0
	v_add_u32_e32 v66, 0, v66
	v_lshlrev_b32_e32 v67, 1, v139
	v_mul_u32_u24_e32 v68, 0x240, v140
	v_add3_u32 v67, v66, v67, v68
	s_waitcnt lgkmcnt(0)
	s_barrier
; __device__ __forceinline__ bf16_t f2bf(float f) { return (bf16_t)(pack2(f, 0.f) & 0xffffu); }
; __device__ __forceinline__ void gemm_late_tile(const Params& p, int l, int mt_, int nt_, unsigned char* smem) {
;     ...
; #pragma unroll
;     for (int i = 0; i < 4; ++i) {
; #pragma unroll
;       for (int j = 0; j < 4; ++j) {
;         const int r = m0 + wr * 64 + i * 16 + fq * 4 + j;
;         const int pp = r % TPB;
;         float v0 = acc[i][0][j], v1 = acc[i][1][j], v2 = acc[i][2][j], v3 = acc[i][3][j];
;         if (cbase < 512 && pp >= 256) {
;           const int tt = pp - 256, rp = tt >> 6, cp = tt & 63;
;           const float2 cs0 = *(const float2*)(p.rope + (rp * 16 + fr) * 2);
;           const float2 cs1 = *(const float2*)(p.rope + (cp * 16 + fr) * 2);
;           float n0_ = v0 * cs0.x - v1 * cs0.y, n1_ = v0 * cs0.y + v1 * cs0.x;
;           float n2_ = v2 * cs1.x - v3 * cs1.y, n3_ = v2 * cs1.y + v3 * cs1.x;
;           v0 = n0_; v1 = n1_; v2 = n2_; v3 = n3_;
;         }
;         if (cbase < 384) { v0 *= 0.125f; v1 *= 0.125f; v2 *= 0.125f; v3 *= 0.125f; }
;         bf16_t* o = wbuf + (i * 16 + fq * 4 + j) * 72 + fr;
;         o[0] = f2bf(v0); o[16] = f2bf(v1); o[32] = f2bf(v2); o[48] = f2bf(v3);
;       }
;     }
;     __builtin_amdgcn_wave_barrier();
;     {
;       const int ch = lane & 7;
;       const bool chv = (cbase + ch * 8) < 3600;
;       const bool halo = (cbase >= 2688) && (cbase + 64 <= 3584);
; #pragma unroll
;       for (int t = 0; t < 8; ++t) {
;         const int rl = (lane >> 3) + 8 * t;
;         const uint4 v = *(const uint4*)(wbuf + rl * 72 + ch * 8);
;         const int r = m0 + wr * 64 + rl;
;         if (chv) *(uint4*)(dst + (size_t)r * ld + coff + ch * 8) = v;
;         if (halo) {
;           const int pp = r % TPB, q34 = pp % 34, t34 = pp / 34, bb = r / TPB;
;           if (q34 == 33 && t34 + 1 < 128) *(uint4*)(p.HALO + ((size_t)(bb * 128 + t34 + 1) * 2 + 0) * 896 + coff + ch * 8) = v;
;           if (q34 == 0 && t34 >= 1) *(uint4*)(p.HALO + ((size_t)(bb * 128 + t34 - 1) * 2 + 1) * 896 + coff + ch * 8) = v;
;         }
;       }
;     }
	ds_write_b16 v67, v48 offset:96
	v_cvt_pk_bf16_f32 v48, v61, s0
	ds_write_b16 v67, v32 offset:2400
	v_cvt_pk_bf16_f32 v32, v45, s0
	ds_write_b16 v67, v16 offset:4704
	v_cvt_pk_bf16_f32 v16, v29, s0
	ds_write_b16 v67, v0 offset:7008
	v_cvt_pk_bf16_f32 v0, v13, s0
	ds_write_b16 v67, v48 offset:144
	v_cvt_pk_bf16_f32 v48, v57, s0
	ds_write_b16 v67, v32 offset:2448
	v_cvt_pk_bf16_f32 v32, v41, s0
	ds_write_b16 v67, v16 offset:4752
	v_cvt_pk_bf16_f32 v16, v25, s0
	ds_write_b16 v67, v0 offset:7056
	v_cvt_pk_bf16_f32 v0, v9, s0
	ds_write_b16 v67, v48 offset:176
	v_cvt_pk_bf16_f32 v48, v53, s0
	ds_write_b16 v67, v32 offset:2480
	v_cvt_pk_bf16_f32 v32, v37, s0
	ds_write_b16 v67, v16 offset:4784
	v_cvt_pk_bf16_f32 v16, v21, s0
	ds_write_b16 v67, v0 offset:7088
	v_cvt_pk_bf16_f32 v0, v5, s0
	ds_write_b16 v67, v48 offset:208
	v_cvt_pk_bf16_f32 v48, v49, s0
	ds_write_b16 v67, v32 offset:2512
	v_cvt_pk_bf16_f32 v32, v33, s0
	ds_write_b16 v67, v16 offset:4816
	v_cvt_pk_bf16_f32 v16, v17, s0
	ds_write_b16 v67, v0 offset:7120
	v_cvt_pk_bf16_f32 v0, v1, s0
	ds_write_b16 v67, v48 offset:240
	v_cvt_pk_bf16_f32 v48, v62, s0
	ds_write_b16 v67, v32 offset:2544
	v_cvt_pk_bf16_f32 v32, v46, s0
	ds_write_b16 v67, v16 offset:4848
	v_cvt_pk_bf16_f32 v16, v30, s0
	ds_write_b16 v67, v0 offset:7152
	v_cvt_pk_bf16_f32 v0, v14, s0
	ds_write_b16 v67, v48 offset:288
	v_cvt_pk_bf16_f32 v48, v58, s0
	ds_write_b16 v67, v32 offset:2592
	v_cvt_pk_bf16_f32 v32, v42, s0
	ds_write_b16 v67, v16 offset:4896
	v_cvt_pk_bf16_f32 v16, v26, s0
	ds_write_b16 v67, v0 offset:7200
	v_cvt_pk_bf16_f32 v0, v10, s0
	ds_write_b16 v67, v48 offset:320
	v_cvt_pk_bf16_f32 v48, v54, s0
	ds_write_b16 v67, v32 offset:2624
	v_cvt_pk_bf16_f32 v32, v38, s0
	ds_write_b16 v67, v16 offset:4928
	v_cvt_pk_bf16_f32 v16, v22, s0
	ds_write_b16 v67, v0 offset:7232
	v_cvt_pk_bf16_f32 v0, v6, s0
	ds_write_b16 v67, v48 offset:352
	v_cvt_pk_bf16_f32 v48, v50, s0
	ds_write_b16 v67, v32 offset:2656
	v_cvt_pk_bf16_f32 v32, v34, s0
	ds_write_b16 v67, v16 offset:4960
	v_cvt_pk_bf16_f32 v16, v18, s0
	ds_write_b16 v67, v0 offset:7264
	v_cvt_pk_bf16_f32 v0, v2, s0
	ds_write_b16 v67, v48 offset:384
	v_cvt_pk_bf16_f32 v48, v63, s0
	ds_write_b16 v67, v32 offset:2688
	v_cvt_pk_bf16_f32 v32, v47, s0
	ds_write_b16 v67, v16 offset:4992
	v_cvt_pk_bf16_f32 v16, v31, s0
	ds_write_b16 v67, v0 offset:7296
	v_cvt_pk_bf16_f32 v0, v15, s0
	ds_write_b16 v67, v48 offset:432
	v_cvt_pk_bf16_f32 v48, v59, s0
	ds_write_b16 v67, v32 offset:2736
	v_cvt_pk_bf16_f32 v32, v43, s0
	ds_write_b16 v67, v16 offset:5040
	v_cvt_pk_bf16_f32 v16, v27, s0
	ds_write_b16 v67, v0 offset:7344
	v_cvt_pk_bf16_f32 v0, v11, s0
	ds_write_b16 v67, v48 offset:464
	v_cvt_pk_bf16_f32 v48, v55, s0
	ds_write_b16 v67, v32 offset:2768
	v_cvt_pk_bf16_f32 v32, v39, s0
	ds_write_b16 v67, v16 offset:5072
	v_cvt_pk_bf16_f32 v16, v23, s0
	ds_write_b16 v67, v0 offset:7376
	v_cvt_pk_bf16_f32 v0, v7, s0
	ds_write_b16 v67, v48 offset:496
	v_cvt_pk_bf16_f32 v48, v51, s0
	ds_write_b16 v67, v32 offset:2800
	v_cvt_pk_bf16_f32 v32, v35, s0
	ds_write_b16 v67, v16 offset:5104
	v_cvt_pk_bf16_f32 v16, v19, s0
	ds_write_b16 v67, v0 offset:7408
	v_cvt_pk_bf16_f32 v0, v3, s0
	s_movk_i32 s0, 0x400
	v_mov_b32_e32 v64, s50
	s_cselect_b32 s50, s0, 0x280
	s_add_i32 s48, s48, s54
	v_mov_b32_e32 v65, s49
	ds_write_b16 v67, v0 offset:7440
	v_and_or_b32 v0, v105, 64, s48
	v_mov_b32_e32 v1, v164
	v_lshrrev_b32_e32 v7, 3, v138
	v_lshlrev_b32_e32 v2, 1, v104
	v_lshl_add_u64 v[0:1], v[0:1], 1, v[64:65]
	v_mov_b32_e32 v3, v164
	ds_write_b16 v67, v4 offset:6976
	v_lshl_add_u64 v[4:5], v[0:1], 0, v[2:3]
	v_mul_u32_u24_e32 v0, 0x90, v7
	v_add3_u32 v9, v66, v2, v0
	ds_write_b16 v67, v60
	ds_write_b16 v67, v56 offset:32
	ds_write_b16 v67, v52 offset:64
	ds_write_b16 v67, v48 offset:528
	ds_write_b16 v67, v44 offset:2304
	ds_write_b16 v67, v40 offset:2336
	ds_write_b16 v67, v36 offset:2368
	ds_write_b16 v67, v32 offset:2832
	ds_write_b16 v67, v28 offset:4608
	ds_write_b16 v67, v24 offset:4640
	ds_write_b16 v67, v20 offset:4672
	ds_write_b16 v67, v16 offset:5136
	ds_write_b16 v67, v12 offset:6912
	ds_write_b16 v67, v8 offset:6944
	ds_read_b128 v[0:3], v9
	v_add_u32_e32 v6, s28, v142
	v_or_b32_e32 v8, v6, v7
	v_mad_i64_i32 v[6:7], s[48:49], s50, v8, 0
	v_lshl_add_u64 v[6:7], v[6:7], 1, v[4:5]
	s_waitcnt lgkmcnt(0)
	global_store_dwordx4 v[6:7], v[0:3], off
	ds_read_b128 v[0:3], v9 offset:1152
	v_or_b32_e32 v6, 8, v8
	v_mad_i64_i32 v[6:7], s[48:49], s50, v6, 0
	v_lshl_add_u64 v[6:7], v[6:7], 1, v[4:5]
	s_waitcnt lgkmcnt(0)
	global_store_dwordx4 v[6:7], v[0:3], off
	ds_read_b128 v[0:3], v9 offset:2304
	v_or_b32_e32 v6, 16, v8
	v_mad_i64_i32 v[6:7], s[48:49], s50, v6, 0
	v_lshl_add_u64 v[6:7], v[6:7], 1, v[4:5]
	s_waitcnt lgkmcnt(0)
	global_store_dwordx4 v[6:7], v[0:3], off
	ds_read_b128 v[0:3], v9 offset:3456
	v_or_b32_e32 v6, 24, v8
	v_mad_i64_i32 v[6:7], s[48:49], s50, v6, 0
	v_lshl_add_u64 v[6:7], v[6:7], 1, v[4:5]
	s_waitcnt lgkmcnt(0)
	global_store_dwordx4 v[6:7], v[0:3], off
	ds_read_b128 v[0:3], v9 offset:4608
	v_or_b32_e32 v6, 32, v8
	v_mad_i64_i32 v[6:7], s[48:49], s50, v6, 0
	v_lshl_add_u64 v[6:7], v[6:7], 1, v[4:5]
	s_waitcnt lgkmcnt(0)
	global_store_dwordx4 v[6:7], v[0:3], off
	ds_read_b128 v[0:3], v9 offset:5760
	v_or_b32_e32 v6, 40, v8
	v_mad_i64_i32 v[6:7], s[48:49], s50, v6, 0
	v_lshl_add_u64 v[6:7], v[6:7], 1, v[4:5]
	s_waitcnt lgkmcnt(0)
	global_store_dwordx4 v[6:7], v[0:3], off
	ds_read_b128 v[0:3], v9 offset:6912
	v_or_b32_e32 v6, 48, v8
	v_mad_i64_i32 v[6:7], s[48:49], s50, v6, 0
	v_lshl_add_u64 v[6:7], v[6:7], 1, v[4:5]
	s_waitcnt lgkmcnt(0)
	global_store_dwordx4 v[6:7], v[0:3], off
	ds_read_b128 v[0:3], v9 offset:8064
	v_or_b32_e32 v6, 56, v8
	v_mad_i64_i32 v[6:7], s[48:49], s50, v6, 0
	v_lshl_add_u64 v[4:5], v[6:7], 1, v[4:5]
	s_mov_b64 s[48:49], 0
	s_waitcnt lgkmcnt(0)
	global_store_dwordx4 v[4:5], v[0:3], off
	s_barrier
	s_branch .LBB0_570

; __device__ __forceinline__ void phase_setup(const Params& p, unsigned char* smem) {
;     ...
;       const float* wp = p.ada_w + ((size_t)l * 1024 + kg * 128) * 3072 + n0 + col;
; #pragma unroll 8
;       for (int k = 0; k < 128; ++k) {
;         float w = wp[(size_t)k * 3072];
;         int kk = kg * 128 + k;
;         a0 += cact[kk] * w; a1 += cact[1024 + kk] * w; a2 += cact[2048 + kk] * w; a3 += cact[3072 + kk] * w; a4 += cact[4096 + kk] * w;
;       }
.LBB0_1364:
	v_lshl_add_u64 v[26:27], v[16:17], 0, s[58:59]
	s_waitcnt vmcnt(0)
	v_add_co_u32_e32 v28, vcc, s41, v26
	s_movk_i32 s60, 0x6000
	s_nop 0
	v_addc_co_u32_e32 v29, vcc, 0, v27, vcc
	v_add_co_u32_e32 v30, vcc, s60, v26
	s_mov_b32 s60, 0x9000
	s_nop 0
	v_addc_co_u32_e32 v31, vcc, 0, v27, vcc
	v_add_co_u32_e32 v32, vcc, s60, v26
	s_mov_b32 s60, 0xc000
	s_nop 0
	v_addc_co_u32_e32 v33, vcc, 0, v27, vcc
	global_load_dword v66, v[26:27], off
	v_add_co_u32_e32 v34, vcc, s60, v26
	s_mov_b32 s60, 0xf000
	s_nop 0
	v_addc_co_u32_e32 v35, vcc, 0, v27, vcc
	v_add_co_u32_e32 v36, vcc, s60, v26
	s_mov_b32 s60, 0x12000
	s_nop 0
	v_addc_co_u32_e32 v37, vcc, 0, v27, vcc
	v_add_co_u32_e32 v38, vcc, s60, v26
	s_mov_b32 s60, 0x15000
	s_nop 0
	v_addc_co_u32_e32 v39, vcc, 0, v27, vcc
	v_add_co_u32_e32 v26, vcc, s60, v26
	s_add_u32 s58, s58, 0x18000
	s_nop 0
	v_addc_co_u32_e32 v27, vcc, 0, v27, vcc
	global_load_dword v68, v[28:29], off
	global_load_dword v70, v[30:31], off
	global_load_dword v72, v[32:33], off
	global_load_dword v74, v[34:35], off
	global_load_dword v76, v[36:37], off
	global_load_dword v78, v[38:39], off
	global_load_dword v80, v[26:27], off
	v_lshl_add_u64 v[26:27], v[16:17], 0, s[58:59]
	v_add_co_u32_e32 v28, vcc, s41, v26
	s_movk_i32 s60, 0x6000
	s_nop 0
	v_addc_co_u32_e32 v29, vcc, 0, v27, vcc
	v_add_co_u32_e32 v30, vcc, s60, v26
	s_mov_b32 s60, 0x9000
	s_nop 0
	v_addc_co_u32_e32 v31, vcc, 0, v27, vcc
	v_add_co_u32_e32 v32, vcc, s60, v26
	s_mov_b32 s60, 0xc000
	s_nop 0
	v_addc_co_u32_e32 v33, vcc, 0, v27, vcc
	global_load_dword v86, v[26:27], off
	v_add_co_u32_e32 v34, vcc, s60, v26
	s_mov_b32 s60, 0xf000
	s_nop 0
	v_addc_co_u32_e32 v35, vcc, 0, v27, vcc
	v_add_co_u32_e32 v36, vcc, s60, v26
	s_mov_b32 s60, 0x12000
	s_nop 0
	v_addc_co_u32_e32 v37, vcc, 0, v27, vcc
	v_add_co_u32_e32 v38, vcc, s60, v26
	s_mov_b32 s60, 0x15000
	s_nop 0
	v_addc_co_u32_e32 v39, vcc, 0, v27, vcc
	v_add_co_u32_e32 v26, vcc, s60, v26
	s_add_u32 s58, s58, 0x18000
	s_nop 0
	v_addc_co_u32_e32 v27, vcc, 0, v27, vcc
	global_load_dword v88, v[28:29], off
	global_load_dword v90, v[30:31], off
	global_load_dword v92, v[32:33], off
	global_load_dword v94, v[34:35], off
	global_load_dword v96, v[36:37], off
	global_load_dword v98, v[38:39], off
	global_load_dword v100, v[26:27], off
	v_lshl_add_u64 v[26:27], v[16:17], 0, s[58:59]
	v_add_co_u32_e32 v28, vcc, s41, v26
	s_movk_i32 s60, 0x6000
	s_nop 0
	v_addc_co_u32_e32 v29, vcc, 0, v27, vcc
	v_add_co_u32_e32 v30, vcc, s60, v26
	s_mov_b32 s60, 0x9000
	s_nop 0
	v_addc_co_u32_e32 v31, vcc, 0, v27, vcc
	v_add_co_u32_e32 v32, vcc, s60, v26
	s_mov_b32 s60, 0xc000
	s_nop 0
	v_addc_co_u32_e32 v33, vcc, 0, v27, vcc
	global_load_dword v106, v[26:27], off
	v_add_co_u32_e32 v34, vcc, s60, v26
	s_mov_b32 s60, 0xf000
	s_nop 0
	v_addc_co_u32_e32 v35, vcc, 0, v27, vcc
	v_add_co_u32_e32 v36, vcc, s60, v26
	s_mov_b32 s60, 0x12000
	s_nop 0
	v_addc_co_u32_e32 v37, vcc, 0, v27, vcc
	v_add_co_u32_e32 v38, vcc, s60, v26
	s_mov_b32 s60, 0x15000
	s_nop 0
	v_addc_co_u32_e32 v39, vcc, 0, v27, vcc
	v_add_co_u32_e32 v26, vcc, s60, v26
	s_add_u32 s58, s58, 0x18000
	s_nop 0
	v_addc_co_u32_e32 v27, vcc, 0, v27, vcc
	global_load_dword v108, v[28:29], off
	global_load_dword v110, v[30:31], off
	global_load_dword v112, v[32:33], off
	global_load_dword v114, v[34:35], off
	global_load_dword v116, v[36:37], off
	global_load_dword v118, v[38:39], off
	global_load_dword v120, v[26:27], off
	v_lshl_add_u64 v[26:27], v[16:17], 0, s[58:59]
	v_add_co_u32_e32 v28, vcc, s41, v26
	s_movk_i32 s60, 0x6000
	s_nop 0
	v_addc_co_u32_e32 v29, vcc, 0, v27, vcc
	v_add_co_u32_e32 v30, vcc, s60, v26
	s_mov_b32 s60, 0x9000
	s_nop 0
	v_addc_co_u32_e32 v31, vcc, 0, v27, vcc
	v_add_co_u32_e32 v32, vcc, s60, v26
	s_mov_b32 s60, 0xc000
	s_nop 0
	v_addc_co_u32_e32 v33, vcc, 0, v27, vcc
	global_load_dword v126, v[26:27], off
	v_add_co_u32_e32 v34, vcc, s60, v26
	s_mov_b32 s60, 0xf000
	s_nop 0
	v_addc_co_u32_e32 v35, vcc, 0, v27, vcc
	v_add_co_u32_e32 v36, vcc, s60, v26
	s_mov_b32 s60, 0x12000
	s_nop 0
	v_addc_co_u32_e32 v37, vcc, 0, v27, vcc
	v_add_co_u32_e32 v38, vcc, s60, v26
	s_mov_b32 s60, 0x15000
	s_nop 0
	v_addc_co_u32_e32 v39, vcc, 0, v27, vcc
	v_add_co_u32_e32 v26, vcc, s60, v26
	s_add_u32 s58, s58, 0x18000
	s_nop 0
	v_addc_co_u32_e32 v27, vcc, 0, v27, vcc
	global_load_dword v128, v[28:29], off
	global_load_dword v130, v[30:31], off
	global_load_dword v132, v[32:33], off
	global_load_dword v134, v[34:35], off
	global_load_dword v136, v[36:37], off
	global_load_dword v138, v[38:39], off
	global_load_dword v140, v[26:27], off
	ds_read_b128 v[26:29], v15
	ds_read_b128 v[30:33], v15 offset:16
	ds_read_b128 v[34:37], v15 offset:4096
	ds_read_b128 v[38:41], v15 offset:4112
	ds_read_b128 v[42:45], v15 offset:8192
	ds_read_b128 v[46:49], v15 offset:8208
	ds_read_b128 v[50:53], v15 offset:12288
	ds_read_b128 v[54:57], v15 offset:12304
	ds_read_b128 v[58:61], v15 offset:16384
	ds_read_b128 v[62:65], v15 offset:16400
	s_waitcnt lgkmcnt(9)
	v_mov_b32_e32 v82, v26
	s_waitcnt lgkmcnt(7)
	v_mov_b32_e32 v83, v34
	s_waitcnt lgkmcnt(5)
	v_mov_b32_e32 v84, v42
	s_waitcnt lgkmcnt(3)
	v_mov_b32_e32 v85, v50
	v_mov_b32_e32 v34, v27
	v_mov_b32_e32 v50, v43
	v_mov_b32_e32 v26, v28
	v_mov_b32_e32 v27, v36
	v_mov_b32_e32 v42, v44
	v_mov_b32_e32 v43, v52
	v_mov_b32_e32 v36, v29
	v_mov_b32_e32 v52, v45
	v_mov_b32_e32 v28, v30
	v_mov_b32_e32 v29, v38
	v_mov_b32_e32 v44, v46
	s_waitcnt lgkmcnt(2)
	v_mov_b32_e32 v45, v54
	v_mov_b32_e32 v38, v31
	v_mov_b32_e32 v54, v47
	v_mov_b32_e32 v30, v32
	v_mov_b32_e32 v31, v40
	v_mov_b32_e32 v46, v48
	v_mov_b32_e32 v47, v56
	v_mov_b32_e32 v40, v33
	v_mov_b32_e32 v56, v49
	v_add_u32_e32 v15, 32, v15
	s_waitcnt vmcnt(31)
; __device__ __forceinline__ void phase_setup(const Params& p, unsigned char* smem) {
;     ...
;       const float* wp = p.ada_w + ((size_t)l * 1024 + kg * 128) * 3072 + n0 + col;
; #pragma unroll 8
;       for (int k = 0; k < 128; ++k) {
;         float w = wp[(size_t)k * 3072];
;         int kk = kg * 128 + k;
;         a0 += cact[kk] * w; a1 += cact[1024 + kk] * w; a2 += cact[2048 + kk] * w; a3 += cact[3072 + kk] * w; a4 += cact[4096 + kk] * w;
;       }
	v_pk_fma_f32 v[18:19], v[66:67], v[82:83], v[18:19] op_sel_hi:[0,1,1]
	v_pk_fma_f32 v[20:21], v[66:67], v[84:85], v[20:21] op_sel_hi:[0,1,1]
	s_waitcnt lgkmcnt(1)
	v_fmac_f32_e32 v1, v66, v58
	s_waitcnt vmcnt(30)
	v_pk_fma_f32 v[18:19], v[68:69], v[34:35], v[18:19] op_sel_hi:[0,1,1]
	v_pk_fma_f32 v[20:21], v[68:69], v[50:51], v[20:21] op_sel_hi:[0,1,1]
	v_fmac_f32_e32 v1, v68, v59
	s_waitcnt vmcnt(29)
	v_pk_fma_f32 v[18:19], v[70:71], v[26:27], v[18:19] op_sel_hi:[0,1,1]
	v_pk_fma_f32 v[20:21], v[70:71], v[42:43], v[20:21] op_sel_hi:[0,1,1]
	v_fmac_f32_e32 v1, v70, v60
	s_waitcnt vmcnt(28)
	v_pk_fma_f32 v[18:19], v[72:73], v[36:37], v[18:19] op_sel_hi:[0,1,1]
	v_pk_fma_f32 v[20:21], v[72:73], v[52:53], v[20:21] op_sel_hi:[0,1,1]
	v_fmac_f32_e32 v1, v72, v61
	s_waitcnt vmcnt(27)
	v_pk_fma_f32 v[18:19], v[74:75], v[28:29], v[18:19] op_sel_hi:[0,1,1]
	v_pk_fma_f32 v[20:21], v[74:75], v[44:45], v[20:21] op_sel_hi:[0,1,1]
	s_waitcnt lgkmcnt(0)
	v_fmac_f32_e32 v1, v74, v62
	s_waitcnt vmcnt(26)
	v_pk_fma_f32 v[18:19], v[76:77], v[38:39], v[18:19] op_sel_hi:[0,1,1]
	v_pk_fma_f32 v[20:21], v[76:77], v[54:55], v[20:21] op_sel_hi:[0,1,1]
	v_fmac_f32_e32 v1, v76, v63
	s_waitcnt vmcnt(25)
	v_pk_fma_f32 v[18:19], v[78:79], v[30:31], v[18:19] op_sel_hi:[0,1,1]
	v_pk_fma_f32 v[20:21], v[78:79], v[46:47], v[20:21] op_sel_hi:[0,1,1]
	v_fmac_f32_e32 v1, v78, v64
	s_waitcnt vmcnt(24)
	v_pk_fma_f32 v[18:19], v[80:81], v[40:41], v[18:19] op_sel_hi:[0,1,1]
	v_pk_fma_f32 v[20:21], v[80:81], v[56:57], v[20:21] op_sel_hi:[0,1,1]
	v_fmac_f32_e32 v1, v80, v65
	ds_read_b128 v[26:29], v15
	ds_read_b128 v[30:33], v15 offset:16
	ds_read_b128 v[34:37], v15 offset:4096
	ds_read_b128 v[38:41], v15 offset:4112
	ds_read_b128 v[42:45], v15 offset:8192
	ds_read_b128 v[46:49], v15 offset:8208
	ds_read_b128 v[50:53], v15 offset:12288
	ds_read_b128 v[54:57], v15 offset:12304
	ds_read_b128 v[58:61], v15 offset:16384
	ds_read_b128 v[62:65], v15 offset:16400
	s_waitcnt lgkmcnt(9)
	v_mov_b32_e32 v82, v26
	s_waitcnt lgkmcnt(7)
	v_mov_b32_e32 v83, v34
	s_waitcnt lgkmcnt(5)
	v_mov_b32_e32 v84, v42
	s_waitcnt lgkmcnt(3)
	v_mov_b32_e32 v85, v50
	v_mov_b32_e32 v34, v27
	v_mov_b32_e32 v50, v43
	v_mov_b32_e32 v26, v28
	v_mov_b32_e32 v27, v36
	v_mov_b32_e32 v42, v44
	v_mov_b32_e32 v43, v52
	v_mov_b32_e32 v36, v29
	v_mov_b32_e32 v52, v45
	v_mov_b32_e32 v28, v30
	v_mov_b32_e32 v29, v38
	v_mov_b32_e32 v44, v46
	s_waitcnt lgkmcnt(2)
	v_mov_b32_e32 v45, v54
	v_mov_b32_e32 v38, v31
	v_mov_b32_e32 v54, v47
	v_mov_b32_e32 v30, v32
	v_mov_b32_e32 v31, v40
	v_mov_b32_e32 v46, v48
	v_mov_b32_e32 v47, v56
	v_mov_b32_e32 v40, v33
	v_mov_b32_e32 v56, v49
	v_add_u32_e32 v15, 32, v15
	s_waitcnt vmcnt(23)
	v_pk_fma_f32 v[18:19], v[86:87], v[82:83], v[18:19] op_sel_hi:[0,1,1]
	v_pk_fma_f32 v[20:21], v[86:87], v[84:85], v[20:21] op_sel_hi:[0,1,1]
	s_waitcnt lgkmcnt(1)
	v_fmac_f32_e32 v1, v86, v58
	s_waitcnt vmcnt(22)
	v_pk_fma_f32 v[18:19], v[88:89], v[34:35], v[18:19] op_sel_hi:[0,1,1]
	v_pk_fma_f32 v[20:21], v[88:89], v[50:51], v[20:21] op_sel_hi:[0,1,1]
	v_fmac_f32_e32 v1, v88, v59
	s_waitcnt vmcnt(21)
	v_pk_fma_f32 v[18:19], v[90:91], v[26:27], v[18:19] op_sel_hi:[0,1,1]
	v_pk_fma_f32 v[20:21], v[90:91], v[42:43], v[20:21] op_sel_hi:[0,1,1]
	v_fmac_f32_e32 v1, v90, v60
	s_waitcnt vmcnt(20)
	v_pk_fma_f32 v[18:19], v[92:93], v[36:37], v[18:19] op_sel_hi:[0,1,1]
	v_pk_fma_f32 v[20:21], v[92:93], v[52:53], v[20:21] op_sel_hi:[0,1,1]
	v_fmac_f32_e32 v1, v92, v61
	s_waitcnt vmcnt(19)
	v_pk_fma_f32 v[18:19], v[94:95], v[28:29], v[18:19] op_sel_hi:[0,1,1]
	v_pk_fma_f32 v[20:21], v[94:95], v[44:45], v[20:21] op_sel_hi:[0,1,1]
	s_waitcnt lgkmcnt(0)
	v_fmac_f32_e32 v1, v94, v62
	s_waitcnt vmcnt(18)
	v_pk_fma_f32 v[18:19], v[96:97], v[38:39], v[18:19] op_sel_hi:[0,1,1]
	v_pk_fma_f32 v[20:21], v[96:97], v[54:55], v[20:21] op_sel_hi:[0,1,1]
	v_fmac_f32_e32 v1, v96, v63
	s_waitcnt vmcnt(17)
	v_pk_fma_f32 v[18:19], v[98:99], v[30:31], v[18:19] op_sel_hi:[0,1,1]
	v_pk_fma_f32 v[20:21], v[98:99], v[46:47], v[20:21] op_sel_hi:[0,1,1]
	v_fmac_f32_e32 v1, v98, v64
	s_waitcnt vmcnt(16)
	v_pk_fma_f32 v[18:19], v[100:101], v[40:41], v[18:19] op_sel_hi:[0,1,1]
	v_pk_fma_f32 v[20:21], v[100:101], v[56:57], v[20:21] op_sel_hi:[0,1,1]
	v_fmac_f32_e32 v1, v100, v65
	ds_read_b128 v[26:29], v15
	ds_read_b128 v[30:33], v15 offset:16
	ds_read_b128 v[34:37], v15 offset:4096
	ds_read_b128 v[38:41], v15 offset:4112
	ds_read_b128 v[42:45], v15 offset:8192
	ds_read_b128 v[46:49], v15 offset:8208
	ds_read_b128 v[50:53], v15 offset:12288
	ds_read_b128 v[54:57], v15 offset:12304
	ds_read_b128 v[58:61], v15 offset:16384
	ds_read_b128 v[62:65], v15 offset:16400
	s_waitcnt lgkmcnt(9)
	v_mov_b32_e32 v82, v26
	s_waitcnt lgkmcnt(7)
	v_mov_b32_e32 v83, v34
	s_waitcnt lgkmcnt(5)
	v_mov_b32_e32 v84, v42
	s_waitcnt lgkmcnt(3)
	v_mov_b32_e32 v85, v50
	v_mov_b32_e32 v34, v27
	v_mov_b32_e32 v50, v43
	v_mov_b32_e32 v26, v28
	v_mov_b32_e32 v27, v36
	v_mov_b32_e32 v42, v44
	v_mov_b32_e32 v43, v52
	v_mov_b32_e32 v36, v29
	v_mov_b32_e32 v52, v45
	v_mov_b32_e32 v28, v30
	v_mov_b32_e32 v29, v38
	v_mov_b32_e32 v44, v46
	s_waitcnt lgkmcnt(2)
	v_mov_b32_e32 v45, v54
	v_mov_b32_e32 v38, v31
	v_mov_b32_e32 v54, v47
	v_mov_b32_e32 v30, v32
	v_mov_b32_e32 v31, v40
	v_mov_b32_e32 v46, v48
	v_mov_b32_e32 v47, v56
	v_mov_b32_e32 v40, v33
	v_mov_b32_e32 v56, v49
	v_add_u32_e32 v15, 32, v15
	s_waitcnt vmcnt(15)
	v_pk_fma_f32 v[18:19], v[106:107], v[82:83], v[18:19] op_sel_hi:[0,1,1]
	v_pk_fma_f32 v[20:21], v[106:107], v[84:85], v[20:21] op_sel_hi:[0,1,1]
	s_waitcnt lgkmcnt(1)
	v_fmac_f32_e32 v1, v106, v58
	s_waitcnt vmcnt(14)
; __device__ __forceinline__ void phase_setup(const Params& p, unsigned char* smem) {
;     ...
;       for (int k = 0; k < 128; ++k) {
;         float w = wp[(size_t)k * 3072];
;         int kk = kg * 128 + k;
;         a0 += cact[kk] * w; a1 += cact[1024 + kk] * w; a2 += cact[2048 + kk] * w; a3 += cact[3072 + kk] * w; a4 += cact[4096 + kk] * w;
;       }
;       float* red = cact + 5120;
;       red[(kg * 5 + 0) * 32 + col] = a0; red[(kg * 5 + 1) * 32 + col] = a1; red[(kg * 5 + 2) * 32 + col] = a2;
;       red[(kg * 5 + 3) * 32 + col] = a3; red[(kg * 5 + 4) * 32 + col] = a4;
;       __syncthreads();
;       if (tid < 160) {
;         int j = tid >> 5, cc = tid & 31;
;         float s = 0;
; #pragma unroll
;         for (int g = 0; g < 8; ++g) s += red[(g * 5 + j) * 32 + cc];
;         p.mod[(size_t)(l * 5 + j) * 3072 + n0 + cc] = s + p.ada_b[l * 3072 + n0 + cc];
	v_pk_fma_f32 v[18:19], v[108:109], v[34:35], v[18:19] op_sel_hi:[0,1,1]
	v_pk_fma_f32 v[20:21], v[108:109], v[50:51], v[20:21] op_sel_hi:[0,1,1]
	v_fmac_f32_e32 v1, v108, v59
	s_waitcnt vmcnt(13)
	v_pk_fma_f32 v[18:19], v[110:111], v[26:27], v[18:19] op_sel_hi:[0,1,1]
	v_pk_fma_f32 v[20:21], v[110:111], v[42:43], v[20:21] op_sel_hi:[0,1,1]
	v_fmac_f32_e32 v1, v110, v60
	s_waitcnt vmcnt(12)
	v_pk_fma_f32 v[18:19], v[112:113], v[36:37], v[18:19] op_sel_hi:[0,1,1]
	v_pk_fma_f32 v[20:21], v[112:113], v[52:53], v[20:21] op_sel_hi:[0,1,1]
	v_fmac_f32_e32 v1, v112, v61
	s_waitcnt vmcnt(11)
	v_pk_fma_f32 v[18:19], v[114:115], v[28:29], v[18:19] op_sel_hi:[0,1,1]
	v_pk_fma_f32 v[20:21], v[114:115], v[44:45], v[20:21] op_sel_hi:[0,1,1]
	s_waitcnt lgkmcnt(0)
	v_fmac_f32_e32 v1, v114, v62
	s_waitcnt vmcnt(10)
	v_pk_fma_f32 v[18:19], v[116:117], v[38:39], v[18:19] op_sel_hi:[0,1,1]
	v_pk_fma_f32 v[20:21], v[116:117], v[54:55], v[20:21] op_sel_hi:[0,1,1]
	v_fmac_f32_e32 v1, v116, v63
	s_waitcnt vmcnt(9)
	v_pk_fma_f32 v[18:19], v[118:119], v[30:31], v[18:19] op_sel_hi:[0,1,1]
	v_pk_fma_f32 v[20:21], v[118:119], v[46:47], v[20:21] op_sel_hi:[0,1,1]
	v_fmac_f32_e32 v1, v118, v64
	s_waitcnt vmcnt(8)
	v_pk_fma_f32 v[18:19], v[120:121], v[40:41], v[18:19] op_sel_hi:[0,1,1]
	v_pk_fma_f32 v[20:21], v[120:121], v[56:57], v[20:21] op_sel_hi:[0,1,1]
	v_fmac_f32_e32 v1, v120, v65
	ds_read_b128 v[26:29], v15
	ds_read_b128 v[30:33], v15 offset:16
	ds_read_b128 v[34:37], v15 offset:4096
	ds_read_b128 v[38:41], v15 offset:4112
	ds_read_b128 v[42:45], v15 offset:8192
	ds_read_b128 v[46:49], v15 offset:8208
	ds_read_b128 v[50:53], v15 offset:12288
	ds_read_b128 v[54:57], v15 offset:12304
	ds_read_b128 v[58:61], v15 offset:16384
	ds_read_b128 v[62:65], v15 offset:16400
	s_waitcnt lgkmcnt(9)
	v_mov_b32_e32 v82, v26
	s_waitcnt lgkmcnt(7)
	v_mov_b32_e32 v83, v34
	s_waitcnt lgkmcnt(5)
	v_mov_b32_e32 v84, v42
	s_waitcnt lgkmcnt(3)
	v_mov_b32_e32 v85, v50
	v_mov_b32_e32 v34, v27
	v_mov_b32_e32 v50, v43
	v_mov_b32_e32 v26, v28
	v_mov_b32_e32 v27, v36
	v_mov_b32_e32 v42, v44
	v_mov_b32_e32 v43, v52
	v_mov_b32_e32 v36, v29
	v_mov_b32_e32 v52, v45
	v_mov_b32_e32 v28, v30
	v_mov_b32_e32 v29, v38
	v_mov_b32_e32 v44, v46
	s_waitcnt lgkmcnt(2)
	v_mov_b32_e32 v45, v54
	v_mov_b32_e32 v38, v31
	v_mov_b32_e32 v54, v47
	v_mov_b32_e32 v30, v32
	v_mov_b32_e32 v31, v40
	v_mov_b32_e32 v46, v48
	v_mov_b32_e32 v47, v56
	v_mov_b32_e32 v40, v33
	v_mov_b32_e32 v56, v49
	v_add_u32_e32 v15, 32, v15
	s_cmp_eq_u32 s58, 0x180000
	s_waitcnt vmcnt(7)
	v_pk_fma_f32 v[18:19], v[126:127], v[82:83], v[18:19] op_sel_hi:[0,1,1]
	v_pk_fma_f32 v[20:21], v[126:127], v[84:85], v[20:21] op_sel_hi:[0,1,1]
	s_waitcnt lgkmcnt(1)
	v_fmac_f32_e32 v1, v126, v58
	s_waitcnt vmcnt(6)
	v_pk_fma_f32 v[18:19], v[128:129], v[34:35], v[18:19] op_sel_hi:[0,1,1]
	v_pk_fma_f32 v[20:21], v[128:129], v[50:51], v[20:21] op_sel_hi:[0,1,1]
	v_fmac_f32_e32 v1, v128, v59
	s_waitcnt vmcnt(5)
	v_pk_fma_f32 v[18:19], v[130:131], v[26:27], v[18:19] op_sel_hi:[0,1,1]
	v_pk_fma_f32 v[20:21], v[130:131], v[42:43], v[20:21] op_sel_hi:[0,1,1]
	v_fmac_f32_e32 v1, v130, v60
	s_waitcnt vmcnt(4)
	v_pk_fma_f32 v[18:19], v[132:133], v[36:37], v[18:19] op_sel_hi:[0,1,1]
	v_pk_fma_f32 v[20:21], v[132:133], v[52:53], v[20:21] op_sel_hi:[0,1,1]
	v_fmac_f32_e32 v1, v132, v61
	s_waitcnt vmcnt(3)
	v_pk_fma_f32 v[18:19], v[134:135], v[28:29], v[18:19] op_sel_hi:[0,1,1]
	v_pk_fma_f32 v[20:21], v[134:135], v[44:45], v[20:21] op_sel_hi:[0,1,1]
	s_waitcnt lgkmcnt(0)
	v_fmac_f32_e32 v1, v134, v62
	s_waitcnt vmcnt(2)
	v_pk_fma_f32 v[18:19], v[136:137], v[38:39], v[18:19] op_sel_hi:[0,1,1]
	v_pk_fma_f32 v[20:21], v[136:137], v[54:55], v[20:21] op_sel_hi:[0,1,1]
	v_fmac_f32_e32 v1, v136, v63
	s_waitcnt vmcnt(1)
	v_pk_fma_f32 v[18:19], v[138:139], v[30:31], v[18:19] op_sel_hi:[0,1,1]
	v_pk_fma_f32 v[20:21], v[138:139], v[46:47], v[20:21] op_sel_hi:[0,1,1]
	v_fmac_f32_e32 v1, v138, v64
	s_waitcnt vmcnt(0)
	v_pk_fma_f32 v[18:19], v[140:141], v[40:41], v[18:19] op_sel_hi:[0,1,1]
	v_pk_fma_f32 v[20:21], v[140:141], v[56:57], v[20:21] op_sel_hi:[0,1,1]
	v_fmac_f32_e32 v1, v140, v65
	s_cbranch_scc0 .LBB0_1364
	v_add_u32_e32 v15, 0x5000, v8
	ds_write2_b32 v15, v18, v19 offset1:32
	ds_write2_b32 v15, v20, v21 offset0:64 offset1:96
	ds_write_b32 v8, v1 offset:20992
	s_waitcnt lgkmcnt(0)
	s_barrier
	s_and_saveexec_b64 s[58:59], s[48:49]
	s_cbranch_execz .LBB0_1367
	s_and_b64 s[60:61], s[56:57], exec
	s_cselect_b32 s60, 0xc00, 0
	s_add_i32 s60, s28, s60
	v_readlane_b32 s68, v253, 36
	v_or_b32_e32 v16, s60, v2
	v_mov_b32_e32 v17, v164
	v_readlane_b32 s78, v253, 46
	v_readlane_b32 s79, v253, 47
	v_add_u32_e32 v18, v6, v4
	v_add_u32_e32 v19, 0x5000, v18
	v_lshl_add_u64 v[16:17], v[16:17], 2, s[78:79]
	global_load_dword v1, v[16:17], off
	v_add_u32_e32 v20, 0x5400, v18
	v_add_u32_e32 v26, 0x5a00, v18
	v_add_u32_e32 v28, 0x5e00, v18
	ds_read2_b32 v[18:19], v19 offset1:160
	ds_read2_b32 v[20:21], v20 offset0:64 offset1:224
	ds_read2_b32 v[26:27], v26 offset1:160
	ds_read2_b32 v[28:29], v28 offset0:64 offset1:224
	v_readlane_b32 s0, v251, 48
	s_waitcnt lgkmcnt(3)
	v_add_f32_e32 v18, 0, v18
	v_add_f32_e32 v18, v18, v19
	s_waitcnt lgkmcnt(2)
	v_add_f32_e32 v18, v18, v20
	s_and_b64 s[56:57], s[56:57], exec
	v_add_f32_e32 v18, v18, v21
	v_readlane_b32 s2, v251, 50
	v_readlane_b32 s3, v251, 51
	s_cselect_b32 s56, 5, 0
	s_waitcnt lgkmcnt(1)
	v_add_f32_e32 v18, v18, v26
	v_mov_b64_e32 v[16:17], s[2:3]
	v_add_u32_e32 v30, s56, v3
	v_add_f32_e32 v18, v18, v27
	v_mad_i64_i32 v[16:17], s[56:57], v30, s41, v[16:17]
	s_waitcnt lgkmcnt(0)
	v_add_f32_e32 v18, v18, v28
	v_mov_b32_e32 v15, v164
	v_lshl_add_u64 v[16:17], s[28:29], 2, v[16:17]
	v_add_f32_e32 v18, v18, v29
	v_lshl_add_u64 v[14:15], v[16:17], 0, v[14:15]
	v_readlane_b32 s69, v253, 37
	v_readlane_b32 s70, v253, 38
	v_readlane_b32 s71, v253, 39
	v_readlane_b32 s72, v253, 40
	v_readlane_b32 s73, v253, 41
	v_readlane_b32 s74, v253, 42
	v_readlane_b32 s75, v253, 43
	v_readlane_b32 s76, v253, 44
	v_readlane_b32 s77, v253, 45
	v_readlane_b32 s80, v253, 48
	v_readlane_b32 s81, v253, 49
	v_readlane_b32 s82, v253, 50
	v_readlane_b32 s83, v253, 51
	v_readlane_b32 s1, v251, 49
	v_readlane_b32 s4, v251, 52
	v_readlane_b32 s5, v251, 53
	v_readlane_b32 s6, v251, 54
	v_readlane_b32 s7, v251, 55
	v_readlane_b32 s8, v251, 56
	v_readlane_b32 s9, v251, 57
	v_readlane_b32 s10, v251, 58
	v_readlane_b32 s11, v251, 59
	v_readlane_b32 s12, v251, 60
	v_readlane_b32 s13, v251, 61
	v_readlane_b32 s14, v251, 62
	v_readlane_b32 s15, v251, 63
	s_waitcnt vmcnt(0)
	v_add_f32_e32 v1, v18, v1
	global_store_dword v[14:15], v1, off
